# v19: s_waitcnt per two LDS fragments in ring code; s_setprio 1 around the QK/PV MFMA sections of both attention loops
# speedup vs baseline: 1.0021x; 1.0021x over previous
; template <int MODE>
; DI void attn_item(const Params& p, int item, char* smem, u16* gdst) {
;     ...
;     if (active && jt < myt) {
;       f32x4 s[2][4];
; #pragma unroll
;       for (int qt = 0; qt < 2; ++qt) {
;         const float nb_ = (jt == 0) ? 0.f : -mrow[qt];
; #pragma unroll
;         for (int kt = 0; kt < 4; ++kt) s[qt][kt] = (f32x4){nb_, nb_, nb_, nb_};
;       }
; #pragma unroll
;       for (int kt = 0; kt < 4; ++kt) {
; #pragma unroll
;         for (int ks = 0; ks < NKS; ++ks) {
;           bf16x8 kf = *(const bf16x8*)(sK + (kt * 16 + fr) * KSTR + (ks >> 1) * 64 + ((ks & 1) ? ko1 : ko0));
;           s[0][kt] = __builtin_amdgcn_mfma_f32_16x16x32_bf16(kf, qf[0][ks], s[0][kt], 0, 0, 0);
;           s[1][kt] = __builtin_amdgcn_mfma_f32_16x16x32_bf16(kf, qf[1][ks], s[1][kt], 0, 0, 0);
;         }
;       }
.Ldsa_qk_main:
	s_cmp_eq_u32 s4, 0
	s_cselect_b64 s[4:5], -1, 0
	v_cndmask_b32_e64 v124, -v207, 0, s[4:5]
	v_cndmask_b32_e64 v140, -v205, 0, s[4:5]
	v_mov_b32_e32 v125, v124
	v_mov_b32_e32 v126, v124
	v_mov_b32_e32 v127, v124
	v_mov_b32_e32 v141, v140
	v_mov_b32_e32 v142, v140
	v_mov_b32_e32 v143, v140
	s_movk_i32 s0, 0xff80
	s_setprio 1
	s_waitcnt lgkmcnt(3)
	v_mfma_f32_16x16x32_bf16 v[128:131], v[232:235], v[44:47], v[124:127]
	v_mfma_f32_16x16x32_bf16 v[112:115], v[232:235], v[64:67], v[140:143]
	ds_read_b128 v[232:235], v137
	v_mfma_f32_16x16x32_bf16 v[128:131], v[236:239], v[52:55], v[128:131]
	v_mfma_f32_16x16x32_bf16 v[112:115], v[236:239], v[68:71], v[112:115]
	ds_read_b128 v[236:239], v136 offset:128
	s_waitcnt lgkmcnt(3)
	v_mfma_f32_16x16x32_bf16 v[128:131], v[240:243], v[56:59], v[128:131]
	v_mfma_f32_16x16x32_bf16 v[112:115], v[240:243], v[72:75], v[112:115]
	ds_read_b128 v[240:243], v137 offset:128
	v_mfma_f32_16x16x32_bf16 v[128:131], v[244:247], v[60:63], v[128:131]
	v_mfma_f32_16x16x32_bf16 v[112:115], v[244:247], v[76:79], v[112:115]
	v_add_u32_e32 v147, s60, v200
	v_add_u32_e32 v157, v147, v196
	v_add_u32_e32 v147, v147, v198
	ds_read_b128 v[244:247], v157
	s_waitcnt lgkmcnt(3)
	v_mfma_f32_16x16x32_bf16 v[132:135], v[248:251], v[44:47], v[124:127]
	v_mfma_f32_16x16x32_bf16 v[116:119], v[248:251], v[64:67], v[140:143]
	ds_read_b128 v[248:251], v147
	v_mfma_f32_16x16x32_bf16 v[132:135], v[232:235], v[52:55], v[132:135]
	v_mfma_f32_16x16x32_bf16 v[116:119], v[232:235], v[68:71], v[116:119]
	ds_read_b128 v[232:235], v157 offset:128
	s_waitcnt lgkmcnt(3)
	v_mfma_f32_16x16x32_bf16 v[132:135], v[236:239], v[56:59], v[132:135]
	v_mfma_f32_16x16x32_bf16 v[116:119], v[236:239], v[72:75], v[116:119]
	ds_read_b128 v[236:239], v147 offset:128
	v_mfma_f32_16x16x32_bf16 v[132:135], v[240:243], v[60:63], v[132:135]
	v_mfma_f32_16x16x32_bf16 v[116:119], v[240:243], v[76:79], v[116:119]
	v_add_u32_e32 v147, s60, v201
	v_add_u32_e32 v157, v147, v196
	v_add_u32_e32 v147, v147, v198
	ds_read_b128 v[240:243], v157
	s_waitcnt lgkmcnt(3)
	v_mfma_f32_16x16x32_bf16 v[136:139], v[244:247], v[44:47], v[124:127]
	v_mfma_f32_16x16x32_bf16 v[120:123], v[244:247], v[64:67], v[140:143]
	ds_read_b128 v[244:247], v147
	v_mfma_f32_16x16x32_bf16 v[136:139], v[248:251], v[52:55], v[136:139]
	v_mfma_f32_16x16x32_bf16 v[120:123], v[248:251], v[68:71], v[120:123]
	ds_read_b128 v[248:251], v157 offset:128
	s_waitcnt lgkmcnt(3)
	v_mfma_f32_16x16x32_bf16 v[136:139], v[232:235], v[56:59], v[136:139]
	v_mfma_f32_16x16x32_bf16 v[120:123], v[232:235], v[72:75], v[120:123]
	ds_read_b128 v[232:235], v147 offset:128
	v_mfma_f32_16x16x32_bf16 v[136:139], v[236:239], v[60:63], v[136:139]
	v_mfma_f32_16x16x32_bf16 v[120:123], v[236:239], v[76:79], v[120:123]
	v_sub_u32_e32 v147, s61, v203
	v_add_u32_e32 v147, 63, v147
	s_waitcnt lgkmcnt(2)
	v_mfma_f32_16x16x32_bf16 v[252:255], v[240:243], v[64:67], v[140:143]
	v_mfma_f32_16x16x32_bf16 v[140:143], v[240:243], v[44:47], v[124:127]
	v_cmp_lt_i32_e32 vcc, s0, v147
	v_mfma_f32_16x16x32_bf16 v[140:143], v[244:247], v[52:55], v[140:143]
	v_mfma_f32_16x16x32_bf16 v[252:255], v[244:247], v[68:71], v[252:255]
	s_waitcnt lgkmcnt(0)
	v_mfma_f32_16x16x32_bf16 v[140:143], v[248:251], v[56:59], v[140:143]
	v_mfma_f32_16x16x32_bf16 v[252:255], v[248:251], v[72:75], v[252:255]
	v_mfma_f32_16x16x32_bf16 v[140:143], v[232:235], v[60:63], v[140:143]
	v_mfma_f32_16x16x32_bf16 v[124:127], v[232:235], v[76:79], v[252:255]
	s_setprio 0
	s_and_saveexec_b64 s[18:19], vcc
	s_cbranch_execz .LBB0_1571
; template <int MODE>
; DI void attn_item(const Params& p, int item, char* smem, u16* gdst) {
;     ...
;         const bool far = (key0 + 63) - (qpos0 + wq0) <= -128;
;         if (!far) {
; #pragma unroll
;           for (int qt = 0; qt < 2; ++qt) {
;             const int rb = key0 + fq * 4 - (qpos0 + qrow[qt]) + 128;
; #pragma unroll
;             for (int kt = 0; kt < 4; ++kt)
; #pragma unroll
;               for (int j = 0; j < 4; ++j) {
;                 int r = min(max(rb + kt * 16 + j, 0), 256);
;                 s[qt][kt][j] += sBias[r];
;               }
;           }
;         }
	v_add_u32_e32 v147, s61, v192
	v_sub_u32_e32 v157, v147, v185
	s_nop 1
	v_max_i32_e32 v169, -1, v157
	v_add_u32_e32 v169, 1, v169
	v_med3_i32 v168, v157, 0, v180
	v_min_u32_e32 v169, 0x100, v169
	v_lshl_add_u32 v168, v168, 2, s34
	v_lshl_add_u32 v169, v169, 2, s34
	ds_read_b32 v168, v168
	ds_read_b32 v169, v169
	v_max_i32_e32 v170, -2, v157
	v_max_i32_e32 v171, -3, v157
	v_add_u32_e32 v170, 2, v170
	v_add_u32_e32 v171, 3, v171
	v_min_u32_e32 v170, 0x100, v170
	v_min_u32_e32 v171, 0x100, v171
	v_lshl_add_u32 v170, v170, 2, s34
	v_lshl_add_u32 v171, v171, 2, s34
	ds_read_b32 v170, v170
	ds_read_b32 v171, v171
	s_waitcnt lgkmcnt(2)
	v_pk_add_f32 v[128:129], v[128:129], v[168:169]
	v_max_i32_e32 v168, -16, v157
	v_max_i32_e32 v169, 0xffffffef, v157
	v_add_u32_e32 v168, 16, v168
	v_add_u32_e32 v169, 17, v169
	v_min_u32_e32 v168, 0x100, v168
	v_min_u32_e32 v169, 0x100, v169
	v_lshl_add_u32 v168, v168, 2, s34
	v_lshl_add_u32 v169, v169, 2, s34
	s_waitcnt lgkmcnt(0)
	v_pk_add_f32 v[130:131], v[130:131], v[170:171]
	ds_read_b32 v168, v168
	ds_read_b32 v169, v169
	v_max_i32_e32 v170, 0xffffffee, v157
	v_max_i32_e32 v171, 0xffffffed, v157
	v_add_u32_e32 v170, 18, v170
	v_add_u32_e32 v171, 19, v171
	v_min_u32_e32 v170, 0x100, v170
	v_min_u32_e32 v171, 0x100, v171
	v_lshl_add_u32 v170, v170, 2, s34
	v_lshl_add_u32 v171, v171, 2, s34
	ds_read_b32 v170, v170
	ds_read_b32 v171, v171
	s_waitcnt lgkmcnt(2)
	v_pk_add_f32 v[132:133], v[132:133], v[168:169]
	v_max_i32_e32 v168, 0xffffffe0, v157
	v_max_i32_e32 v169, 0xffffffdf, v157
	v_add_u32_e32 v168, 32, v168
	v_add_u32_e32 v169, 33, v169
	v_min_u32_e32 v168, 0x100, v168
	v_min_u32_e32 v169, 0x100, v169
	v_lshl_add_u32 v168, v168, 2, s34
	v_lshl_add_u32 v169, v169, 2, s34
	s_waitcnt lgkmcnt(0)
	v_pk_add_f32 v[134:135], v[134:135], v[170:171]
	ds_read_b32 v168, v168
	ds_read_b32 v169, v169
	v_max_i32_e32 v170, 0xffffffde, v157
	v_max_i32_e32 v171, 0xffffffdd, v157
	v_add_u32_e32 v170, 34, v170
	v_add_u32_e32 v171, 35, v171
	v_min_u32_e32 v170, 0x100, v170
	v_min_u32_e32 v171, 0x100, v171
	v_lshl_add_u32 v170, v170, 2, s34
	v_lshl_add_u32 v171, v171, 2, s34
	ds_read_b32 v170, v170
	ds_read_b32 v171, v171
	s_waitcnt lgkmcnt(2)
	v_pk_add_f32 v[136:137], v[136:137], v[168:169]
	v_max_i32_e32 v168, 0xffffffd0, v157
	v_max_i32_e32 v169, 0xffffffcf, v157
	v_add_u32_e32 v168, 48, v168
	v_add_u32_e32 v169, 49, v169
	v_min_u32_e32 v168, 0x100, v168
	v_min_u32_e32 v169, 0x100, v169
	v_lshl_add_u32 v168, v168, 2, s34
	v_lshl_add_u32 v169, v169, 2, s34
	ds_read_b32 v168, v168
	ds_read_b32 v169, v169
	s_waitcnt lgkmcnt(2)
	v_pk_add_f32 v[138:139], v[138:139], v[170:171]
	v_max_i32_e32 v170, 0xffffffce, v157
	v_max_i32_e32 v157, 0xffffffcd, v157
	v_add_u32_e32 v157, 51, v157
	v_min_u32_e32 v157, 0x100, v157
	v_add_u32_e32 v170, 50, v170
	v_lshl_add_u32 v157, v157, 2, s34
	v_sub_u32_e32 v147, v147, v186
	v_min_u32_e32 v170, 0x100, v170
	ds_read_b32 v171, v157
	v_med3_i32 v157, v147, 0, v180
	v_lshl_add_u32 v170, v170, 2, s34
	v_lshl_add_u32 v157, v157, 2, s34
	ds_read_b32 v170, v170
	s_waitcnt lgkmcnt(2)
	v_pk_add_f32 v[140:141], v[140:141], v[168:169]
	ds_read_b32 v168, v157
	v_max_i32_e32 v157, -1, v147
	v_add_u32_e32 v157, 1, v157
	v_min_u32_e32 v157, 0x100, v157
	v_lshl_add_u32 v157, v157, 2, s34
	ds_read_b32 v169, v157
	v_max_i32_e32 v157, -2, v147
	v_add_u32_e32 v157, 2, v157
	v_min_u32_e32 v157, 0x100, v157
	v_lshl_add_u32 v157, v157, 2, s34
	s_waitcnt lgkmcnt(2)
	v_pk_add_f32 v[142:143], v[142:143], v[170:171]
	ds_read_b32 v170, v157
	v_max_i32_e32 v157, -3, v147
	v_add_u32_e32 v157, 3, v157
	v_min_u32_e32 v157, 0x100, v157
	v_lshl_add_u32 v157, v157, 2, s34
	ds_read_b32 v171, v157
	v_max_i32_e32 v157, -16, v147
	v_add_u32_e32 v157, 16, v157
	v_min_u32_e32 v157, 0x100, v157
	v_lshl_add_u32 v157, v157, 2, s34
	s_waitcnt lgkmcnt(2)
	v_pk_add_f32 v[112:113], v[112:113], v[168:169]
	ds_read_b32 v168, v157
	v_max_i32_e32 v157, 0xffffffef, v147
	v_add_u32_e32 v157, 17, v157
	v_min_u32_e32 v157, 0x100, v157
	v_lshl_add_u32 v157, v157, 2, s34
	ds_read_b32 v169, v157
	v_max_i32_e32 v157, 0xffffffee, v147
	v_add_u32_e32 v157, 18, v157
	v_min_u32_e32 v157, 0x100, v157
	v_lshl_add_u32 v157, v157, 2, s34
	s_waitcnt lgkmcnt(2)
	v_pk_add_f32 v[114:115], v[114:115], v[170:171]
	ds_read_b32 v170, v157
	v_max_i32_e32 v157, 0xffffffed, v147
	v_add_u32_e32 v157, 19, v157
	v_min_u32_e32 v157, 0x100, v157
	v_lshl_add_u32 v157, v157, 2, s34
	ds_read_b32 v171, v157
	v_max_i32_e32 v157, 0xffffffe0, v147
	v_add_u32_e32 v157, 32, v157
	v_min_u32_e32 v157, 0x100, v157
	v_lshl_add_u32 v157, v157, 2, s34
	s_waitcnt lgkmcnt(2)
	v_pk_add_f32 v[116:117], v[116:117], v[168:169]
	ds_read_b32 v168, v157
	v_max_i32_e32 v157, 0xffffffdf, v147
	v_add_u32_e32 v157, 33, v157
	v_min_u32_e32 v157, 0x100, v157
	v_lshl_add_u32 v157, v157, 2, s34
	ds_read_b32 v169, v157
	v_max_i32_e32 v157, 0xffffffde, v147
	v_add_u32_e32 v157, 34, v157
	v_min_u32_e32 v157, 0x100, v157
	v_lshl_add_u32 v157, v157, 2, s34
	s_waitcnt lgkmcnt(2)
	v_pk_add_f32 v[118:119], v[118:119], v[170:171]
	ds_read_b32 v170, v157
	v_max_i32_e32 v157, 0xffffffdd, v147
	v_add_u32_e32 v157, 35, v157
	v_min_u32_e32 v157, 0x100, v157
	v_lshl_add_u32 v157, v157, 2, s34
	ds_read_b32 v171, v157
	v_max_i32_e32 v157, 0xffffffd0, v147
	v_add_u32_e32 v157, 48, v157
	v_min_u32_e32 v157, 0x100, v157
	v_lshl_add_u32 v157, v157, 2, s34
	s_waitcnt lgkmcnt(2)
	v_pk_add_f32 v[120:121], v[120:121], v[168:169]
	ds_read_b32 v168, v157
	v_max_i32_e32 v157, 0xffffffcf, v147
	v_add_u32_e32 v157, 49, v157
	v_min_u32_e32 v157, 0x100, v157
	v_lshl_add_u32 v157, v157, 2, s34
	ds_read_b32 v169, v157
	v_max_i32_e32 v157, 0xffffffce, v147
	v_max_i32_e32 v147, 0xffffffcd, v147
	v_add_u32_e32 v157, 50, v157
	v_add_u32_e32 v147, 51, v147
	v_min_u32_e32 v157, 0x100, v157
	v_min_u32_e32 v147, 0x100, v147
	v_lshl_add_u32 v157, v157, 2, s34
	v_lshl_add_u32 v147, v147, 2, s34
	s_waitcnt lgkmcnt(2)
	v_pk_add_f32 v[122:123], v[122:123], v[170:171]
	ds_read_b32 v170, v157
	ds_read_b32 v171, v147
	s_waitcnt lgkmcnt(2)
	v_pk_add_f32 v[124:125], v[124:125], v[168:169]
	s_waitcnt lgkmcnt(0)
	v_pk_add_f32 v[126:127], v[126:127], v[170:171]

; template <int MODE>
; DI void attn_item(const Params& p, int item, char* smem, u16* gdst) {
;     ...
;         for (int s2 = 0; s2 < 2; ++s2) {
;           u32x4 pk;
;           pk[0] = cvtpk(s[qt][2 * s2][0], s[qt][2 * s2][1]);
;           pk[1] = cvtpk(s[qt][2 * s2][2], s[qt][2 * s2][3]);
;           pk[2] = cvtpk(s[qt][2 * s2 + 1][0], s[qt][2 * s2 + 1][1]);
;           pk[3] = cvtpk(s[qt][2 * s2 + 1][2], s[qt][2 * s2 + 1][3]);
;           pf[qt][s2] = __builtin_bit_cast(bf16x8, pk);
;         }
;       }
; #pragma unroll
;       for (int dt = 0; dt < 8; ++dt) {
; #pragma unroll
;         for (int s2 = 0; s2 < 2; ++s2) {
;           const u16* vp = sV + (dt * 16 + fr) * VSTR + fq * 4;
;           u32x2 v0 = *(const u32x2*)(vp + (2 * s2) * 16);
;           u32x2 v1 = *(const u32x2*)(vp + (2 * s2 + 1) * 16);
;           u32x4 vv = {v0[0], v0[1], v1[0], v1[1]};
;           bf16x8 vf = __builtin_bit_cast(bf16x8, vv);
;           o[0][dt] = __builtin_amdgcn_mfma_f32_16x16x32_bf16(vf, pf[0][s2], o[0][dt], 0, 0, 0);
;           o[1][dt] = __builtin_amdgcn_mfma_f32_16x16x32_bf16(vf, pf[1][s2], o[1][dt], 0, 0, 0);
;         }
;       }
.LBB0_1586:
	v_cvt_pk_bf16_f32 v122, v132, v133
	v_cvt_pk_bf16_f32 v123, v134, v135
	v_add3_u32 v133, s60, v190, v202
	ds_read_b64 v[232:233], v133 offset:24576
	ds_read_b64 v[234:235], v133 offset:24608
	ds_read_b64 v[236:237], v133 offset:24640
	ds_read_b64 v[238:239], v133 offset:24672
	ds_read_b64 v[240:241], v133 offset:26880
	ds_read_b64 v[242:243], v133 offset:26912
	ds_read_b64 v[244:245], v133 offset:26944
	ds_read_b64 v[246:247], v133 offset:26976
	ds_read_b64 v[248:249], v133 offset:29184
	ds_read_b64 v[250:251], v133 offset:29216
	ds_read_b64 v[252:253], v133 offset:29248
	ds_read_b64 v[254:255], v133 offset:29280
	v_cvt_pk_bf16_f32 v120, v128, v129
	v_cvt_pk_bf16_f32 v121, v130, v131
	v_add_f32_e32 v124, v205, v214
	v_cndmask_b32_e64 v205, v124, v213, s[4:5]
	v_add_f32_e32 v124, v207, v210
	v_cndmask_b32_e64 v207, v124, v209, s[4:5]
	v_cvt_pk_bf16_f32 v124, v164, v147
	v_cvt_pk_bf16_f32 v125, v170, v157
	v_cvt_pk_bf16_f32 v126, v116, v117
	v_cvt_pk_bf16_f32 v127, v118, v119
	s_setprio 1
	s_waitcnt lgkmcnt(8)
	v_mfma_f32_16x16x32_bf16 v[92:95], v[232:235], v[120:123], v[92:95]
	v_add_f32_e32 v215, v112, v113
	v_cvt_pk_bf16_f32 v112, v136, v137
	v_cvt_pk_bf16_f32 v113, v138, v139
	v_mfma_f32_16x16x32_bf16 v[28:31], v[232:235], v[124:127], v[28:31]
	ds_read_b64 v[232:233], v133 offset:31488
	ds_read_b64 v[234:235], v133 offset:31520
	v_cvt_pk_bf16_f32 v114, v140, v141
	v_cvt_pk_bf16_f32 v115, v142, v143
	v_cvt_pk_bf16_f32 v116, v172, v165
	v_cvt_pk_bf16_f32 v117, v174, v167
	v_cvt_pk_bf16_f32 v118, v176, v169
	v_cvt_pk_bf16_f32 v119, v178, v171
	v_add_f32_e32 v132, v211, v212
	v_fmac_f32_e32 v215, v183, v166
	v_fmac_f32_e32 v132, v208, v168
	v_mfma_f32_16x16x32_bf16 v[92:95], v[236:239], v[112:115], v[92:95]
	v_mov_b32_e32 v208, v132
	v_mov_b32_e32 v183, v215
	v_mfma_f32_16x16x32_bf16 v[28:31], v[236:239], v[116:119], v[28:31]
	ds_read_b64 v[236:237], v133 offset:31552
	ds_read_b64 v[238:239], v133 offset:31584
	s_waitcnt lgkmcnt(8)
	v_mfma_f32_16x16x32_bf16 v[88:91], v[240:243], v[120:123], v[88:91]
	v_mfma_f32_16x16x32_bf16 v[24:27], v[240:243], v[124:127], v[24:27]
	ds_read_b64 v[240:241], v133 offset:33792
	ds_read_b64 v[242:243], v133 offset:33824
	v_mfma_f32_16x16x32_bf16 v[88:91], v[244:247], v[112:115], v[88:91]
	v_mfma_f32_16x16x32_bf16 v[24:27], v[244:247], v[116:119], v[24:27]
	ds_read_b64 v[244:245], v133 offset:33856
	ds_read_b64 v[246:247], v133 offset:33888
	s_waitcnt lgkmcnt(8)
	v_mfma_f32_16x16x32_bf16 v[84:87], v[248:251], v[120:123], v[84:87]
	v_mfma_f32_16x16x32_bf16 v[20:23], v[248:251], v[124:127], v[20:23]
	ds_read_b64 v[248:249], v133 offset:36096
	ds_read_b64 v[250:251], v133 offset:36128
	v_mfma_f32_16x16x32_bf16 v[84:87], v[252:255], v[112:115], v[84:87]
	v_mfma_f32_16x16x32_bf16 v[20:23], v[252:255], v[116:119], v[20:23]
	ds_read_b64 v[252:253], v133 offset:36160
	ds_read_b64 v[254:255], v133 offset:36192
	s_waitcnt lgkmcnt(8)
	v_mfma_f32_16x16x32_bf16 v[80:83], v[232:235], v[120:123], v[80:83]
	v_mfma_f32_16x16x32_bf16 v[16:19], v[232:235], v[124:127], v[16:19]
	ds_read_b64 v[232:233], v133 offset:38400
	ds_read_b64 v[234:235], v133 offset:38432
	v_mfma_f32_16x16x32_bf16 v[80:83], v[236:239], v[112:115], v[80:83]
	v_mfma_f32_16x16x32_bf16 v[16:19], v[236:239], v[116:119], v[16:19]
	ds_read_b64 v[236:237], v133 offset:38464
	ds_read_b64 v[238:239], v133 offset:38496
	s_waitcnt lgkmcnt(8)
	v_mfma_f32_16x16x32_bf16 v[48:51], v[240:243], v[120:123], v[48:51]
	v_mfma_f32_16x16x32_bf16 v[12:15], v[240:243], v[124:127], v[12:15]
	ds_read_b64 v[240:241], v133 offset:40704
	ds_read_b64 v[242:243], v133 offset:40736
	v_mfma_f32_16x16x32_bf16 v[48:51], v[244:247], v[112:115], v[48:51]
	v_mfma_f32_16x16x32_bf16 v[12:15], v[244:247], v[116:119], v[12:15]
	ds_read_b64 v[244:245], v133 offset:40768
	ds_read_b64 v[246:247], v133 offset:40800
	s_waitcnt lgkmcnt(8)
	v_mfma_f32_16x16x32_bf16 v[40:43], v[248:251], v[120:123], v[40:43]
	v_mfma_f32_16x16x32_bf16 v[8:11], v[248:251], v[124:127], v[8:11]
	v_mfma_f32_16x16x32_bf16 v[40:43], v[252:255], v[112:115], v[40:43]
	v_mfma_f32_16x16x32_bf16 v[8:11], v[252:255], v[116:119], v[8:11]
	s_waitcnt lgkmcnt(4)
	v_mfma_f32_16x16x32_bf16 v[36:39], v[232:235], v[120:123], v[36:39]
	v_mfma_f32_16x16x32_bf16 v[4:7], v[232:235], v[124:127], v[4:7]
	v_mfma_f32_16x16x32_bf16 v[36:39], v[236:239], v[112:115], v[36:39]
	v_mfma_f32_16x16x32_bf16 v[4:7], v[236:239], v[116:119], v[4:7]
	s_waitcnt lgkmcnt(0)
	v_mfma_f32_16x16x32_bf16 v[32:35], v[240:243], v[120:123], v[32:35]
	v_mfma_f32_16x16x32_bf16 v[0:3], v[240:243], v[124:127], v[0:3]
	v_mfma_f32_16x16x32_bf16 v[32:35], v[244:247], v[112:115], v[32:35]
	v_mfma_f32_16x16x32_bf16 v[0:3], v[244:247], v[116:119], v[0:3]
	s_setprio 0
	s_or_b64 exec, exec, s[16:17]
	s_cmp_eq_u32 s21, s51
	s_cbranch_scc1 .LBB0_1588

; template <int MODE>
; DI void attn_item(const Params& p, int item, char* smem, u16* gdst) {
;     ...
;     if (active && jt < myt) {
;       f32x4 s[2][4];
; #pragma unroll
;       for (int qt = 0; qt < 2; ++qt) {
;         const float nb_ = (jt == 0) ? 0.f : -mrow[qt];
; #pragma unroll
;         for (int kt = 0; kt < 4; ++kt) s[qt][kt] = (f32x4){nb_, nb_, nb_, nb_};
;       }
; #pragma unroll
;       for (int kt = 0; kt < 4; ++kt) {
; #pragma unroll
;         for (int ks = 0; ks < NKS; ++ks) {
;           bf16x8 kf = *(const bf16x8*)(sK + (kt * 16 + fr) * KSTR + (ks >> 1) * 64 + ((ks & 1) ? ko1 : ko0));
;           s[0][kt] = __builtin_amdgcn_mfma_f32_16x16x32_bf16(kf, qf[0][ks], s[0][kt], 0, 0, 0);
;           s[1][kt] = __builtin_amdgcn_mfma_f32_16x16x32_bf16(kf, qf[1][ks], s[1][kt], 0, 0, 0);
;         }
;       }
.LBB0_1800:
	s_add_i32 s1, s0, 2
	s_min_i32 s1, s1, s13
	s_lshl_b32 s4, s1, 6
	s_add_i32 s6, s4, s12
	s_ashr_i32 s7, s6, 31
	s_waitcnt vmcnt(4)
	v_lshl_add_u64 v[52:53], s[6:7], 0, v[168:169]
	v_lshlrev_b64 v[52:53], 12, v[52:53]
	v_lshl_add_u64 v[52:53], v[2:3], 0, v[52:53]
	s_waitcnt vmcnt(2)
	v_lshl_add_u64 v[60:61], s[6:7], 0, v[170:171]
	s_ashr_i32 s5, s4, 31
	v_add_co_u32_e32 v56, vcc, 0x20000, v52
	v_lshlrev_b64 v[60:61], 7, v[60:61]
	s_waitcnt vmcnt(1)
	v_lshl_add_u64 v[64:65], s[4:5], 1, v[174:175]
	v_addc_co_u32_e32 v57, vcc, 0, v53, vcc
	v_lshl_add_u64 v[60:61], v[176:177], 0, v[60:61]
	s_waitcnt vmcnt(0)
	v_lshl_add_u64 v[68:69], v[64:65], 0, s[10:11]
	global_load_dwordx4 v[52:55], v[52:53], off
	s_nop 0
	global_load_dwordx4 v[56:59], v[56:57], off
	v_cmp_lt_i32_e32 vcc, s0, v185
	global_load_dwordx4 v[60:63], v[60:61], off
	s_nop 0
	global_load_dwordx4 v[64:67], v[64:65], off
	s_nop 0
	global_load_dwordx4 v[68:71], v[68:69], off
	s_and_b64 s[4:5], s[2:3], vcc
	s_and_saveexec_b64 s[14:15], s[4:5]
	s_cbranch_execz .LBB0_1814
	v_xor_b32_e32 v148, 0x80000000, v201
	v_xor_b32_e32 v164, 0x80000000, v203
	v_mov_b32_e32 v149, v148
	v_mov_b32_e32 v150, v148
	v_mov_b32_e32 v151, v148
	v_mov_b32_e32 v165, v164
	v_mov_b32_e32 v166, v164
	v_mov_b32_e32 v167, v164
	s_setprio 1
	s_waitcnt lgkmcnt(3)
	v_mfma_f32_16x16x32_bf16 v[152:155], v[232:235], v[4:7], v[148:151]
	v_mfma_f32_16x16x32_bf16 v[136:139], v[232:235], v[28:31], v[164:167]
	ds_read_b128 v[232:235], v211 offset:256
	v_mfma_f32_16x16x32_bf16 v[152:155], v[236:239], v[8:11], v[152:155]
	v_mfma_f32_16x16x32_bf16 v[136:139], v[236:239], v[32:35], v[136:139]
	v_add_u32_e32 v211, s36, v205
	v_add_u32_e32 v210, v211, v199
	v_add_u32_e32 v211, v211, v191
	ds_read_b128 v[236:239], v210
	s_waitcnt lgkmcnt(3)
	v_mfma_f32_16x16x32_bf16 v[152:155], v[240:243], v[12:15], v[152:155]
	v_mfma_f32_16x16x32_bf16 v[136:139], v[240:243], v[36:39], v[136:139]
	ds_read_b128 v[240:243], v211
	v_mfma_f32_16x16x32_bf16 v[152:155], v[244:247], v[16:19], v[152:155]
	v_mfma_f32_16x16x32_bf16 v[136:139], v[244:247], v[40:43], v[136:139]
	ds_read_b128 v[244:247], v210 offset:128
	s_waitcnt lgkmcnt(3)
	v_mfma_f32_16x16x32_bf16 v[152:155], v[248:251], v[20:23], v[152:155]
	v_mfma_f32_16x16x32_bf16 v[136:139], v[248:251], v[44:47], v[136:139]
	ds_read_b128 v[248:251], v211 offset:128
	v_mfma_f32_16x16x32_bf16 v[152:155], v[232:235], v[24:27], v[152:155]
	v_mfma_f32_16x16x32_bf16 v[136:139], v[232:235], v[48:51], v[136:139]
	ds_read_b128 v[232:235], v210 offset:256
	s_waitcnt lgkmcnt(3)
	v_mfma_f32_16x16x32_bf16 v[156:159], v[236:239], v[4:7], v[148:151]
	v_mfma_f32_16x16x32_bf16 v[140:143], v[236:239], v[28:31], v[164:167]
	ds_read_b128 v[236:239], v211 offset:256
	v_mfma_f32_16x16x32_bf16 v[156:159], v[240:243], v[8:11], v[156:159]
	v_mfma_f32_16x16x32_bf16 v[140:143], v[240:243], v[32:35], v[140:143]
	v_add_u32_e32 v211, s36, v206
	v_add_u32_e32 v210, v211, v199
	v_add_u32_e32 v211, v211, v191
	ds_read_b128 v[240:243], v210
	s_waitcnt lgkmcnt(3)
	v_mfma_f32_16x16x32_bf16 v[156:159], v[244:247], v[12:15], v[156:159]
	v_mfma_f32_16x16x32_bf16 v[140:143], v[244:247], v[36:39], v[140:143]
	ds_read_b128 v[244:247], v211
	v_mfma_f32_16x16x32_bf16 v[156:159], v[248:251], v[16:19], v[156:159]
	v_mfma_f32_16x16x32_bf16 v[140:143], v[248:251], v[40:43], v[140:143]
	ds_read_b128 v[248:251], v210 offset:128
	s_waitcnt lgkmcnt(3)
	v_mfma_f32_16x16x32_bf16 v[156:159], v[232:235], v[20:23], v[156:159]
	v_mfma_f32_16x16x32_bf16 v[140:143], v[232:235], v[44:47], v[140:143]
	ds_read_b128 v[232:235], v211 offset:128
	v_mfma_f32_16x16x32_bf16 v[156:159], v[236:239], v[24:27], v[156:159]
	v_mfma_f32_16x16x32_bf16 v[140:143], v[236:239], v[48:51], v[140:143]
	ds_read_b128 v[236:239], v210 offset:256
	s_waitcnt lgkmcnt(3)
	v_mfma_f32_16x16x32_bf16 v[160:163], v[240:243], v[4:7], v[148:151]
	v_mfma_f32_16x16x32_bf16 v[144:147], v[240:243], v[28:31], v[164:167]
	ds_read_b128 v[240:243], v211 offset:256
	v_mfma_f32_16x16x32_bf16 v[160:163], v[244:247], v[8:11], v[160:163]
	v_mfma_f32_16x16x32_bf16 v[144:147], v[244:247], v[32:35], v[144:147]
	v_add_u32_e32 v211, s36, v207
	v_add_u32_e32 v210, v211, v199
	v_add_u32_e32 v211, v211, v191
	ds_read_b128 v[244:247], v210
	s_waitcnt lgkmcnt(3)
	v_mfma_f32_16x16x32_bf16 v[160:163], v[248:251], v[12:15], v[160:163]
	v_mfma_f32_16x16x32_bf16 v[144:147], v[248:251], v[36:39], v[144:147]
	ds_read_b128 v[248:251], v211
	v_mfma_f32_16x16x32_bf16 v[160:163], v[232:235], v[16:19], v[160:163]
	v_mfma_f32_16x16x32_bf16 v[144:147], v[232:235], v[40:43], v[144:147]
	ds_read_b128 v[232:235], v210 offset:128
	s_waitcnt lgkmcnt(3)
	v_mfma_f32_16x16x32_bf16 v[160:163], v[236:239], v[20:23], v[160:163]
	v_mfma_f32_16x16x32_bf16 v[144:147], v[236:239], v[44:47], v[144:147]
	ds_read_b128 v[236:239], v211 offset:128
	v_mfma_f32_16x16x32_bf16 v[160:163], v[240:243], v[24:27], v[160:163]
	v_mfma_f32_16x16x32_bf16 v[144:147], v[240:243], v[48:51], v[144:147]
	ds_read_b128 v[240:243], v210 offset:256
	s_waitcnt lgkmcnt(3)
	v_mfma_f32_16x16x32_bf16 v[252:255], v[244:247], v[4:7], v[148:151]
	v_mfma_f32_16x16x32_bf16 v[148:151], v[244:247], v[28:31], v[164:167]
	ds_read_b128 v[244:247], v211 offset:256
	v_mfma_f32_16x16x32_bf16 v[252:255], v[248:251], v[8:11], v[252:255]
	v_mfma_f32_16x16x32_bf16 v[148:151], v[248:251], v[32:35], v[148:151]
	s_waitcnt lgkmcnt(2)
	v_mfma_f32_16x16x32_bf16 v[252:255], v[232:235], v[12:15], v[252:255]
	v_mfma_f32_16x16x32_bf16 v[148:151], v[232:235], v[36:39], v[148:151]
	v_mfma_f32_16x16x32_bf16 v[252:255], v[236:239], v[16:19], v[252:255]
	v_mfma_f32_16x16x32_bf16 v[148:151], v[236:239], v[40:43], v[148:151]
	s_waitcnt lgkmcnt(0)
	v_mfma_f32_16x16x32_bf16 v[252:255], v[240:243], v[20:23], v[252:255]
	v_mfma_f32_16x16x32_bf16 v[148:151], v[240:243], v[44:47], v[148:151]
	v_mfma_f32_16x16x32_bf16 v[164:167], v[244:247], v[24:27], v[252:255]
	v_mfma_f32_16x16x32_bf16 v[148:151], v[244:247], v[48:51], v[148:151]
	s_setprio 0
	s_cmp_le_i32 s16, s33
	s_cbranch_scc1 .LBB0_1803
; template <int MODE>
; DI void attn_item(const Params& p, int item, char* smem, u16* gdst) {
;     ...
;       if (MODE == 0) {
;         if (key0 + 64 > nkeys) {
; #pragma unroll
;           for (int kt = 0; kt < 4; ++kt)
; #pragma unroll
;             for (int j = 0; j < 4; ++j)
;               if (key0 + kt * 16 + fq * 4 + j >= nkeys) { s[0][kt][j] = -1e30f; s[1][kt][j] = -1e30f; }
;         }
	v_add_u32_e32 v0, s16, v208
	v_subrev_u32_e32 v209, 64, v0
	v_cmp_gt_i32_e32 vcc, s33, v209
	v_subrev_u32_e32 v209, 63, v0
	v_cmp_gt_i32_e64 s[4:5], s33, v209
	v_subrev_u32_e32 v209, 62, v0
	v_cmp_gt_i32_e64 s[6:7], s33, v209
	v_subrev_u32_e32 v209, 61, v0
	v_cmp_gt_i32_e64 s[8:9], s33, v209
	s_or_b64 s[6:7], s[8:9], s[6:7]
	s_or_b64 s[4:5], s[6:7], s[4:5]
	s_or_b64 vcc, s[4:5], vcc
	v_subrev_u32_e32 v209, 48, v0
	v_cndmask_b32_e32 v136, v183, v136, vcc
	v_cndmask_b32_e32 v152, v183, v152, vcc
	v_cmp_gt_i32_e32 vcc, s33, v209
	v_subrev_u32_e32 v209, 47, v0
	v_cndmask_b32_e64 v137, v183, v137, s[4:5]
	v_cndmask_b32_e64 v153, v183, v153, s[4:5]
	v_cmp_gt_i32_e64 s[4:5], s33, v209
	v_subrev_u32_e32 v209, 46, v0
	v_cndmask_b32_e64 v138, v183, v138, s[6:7]
	v_cndmask_b32_e64 v154, v183, v154, s[6:7]
	v_cmp_gt_i32_e64 s[6:7], s33, v209
	v_subrev_u32_e32 v209, 45, v0
	v_cndmask_b32_e64 v139, v183, v139, s[8:9]
	v_cndmask_b32_e64 v155, v183, v155, s[8:9]
	v_cmp_gt_i32_e64 s[8:9], s33, v209
	s_or_b64 s[6:7], s[8:9], s[6:7]
	s_or_b64 s[4:5], s[6:7], s[4:5]
	s_or_b64 vcc, s[4:5], vcc
	v_subrev_u32_e32 v209, 32, v0
	v_cndmask_b32_e32 v140, v183, v140, vcc
	v_cndmask_b32_e32 v156, v183, v156, vcc
	v_cmp_gt_i32_e32 vcc, s33, v209
	v_subrev_u32_e32 v209, 31, v0
	v_cndmask_b32_e64 v141, v183, v141, s[4:5]
	v_cndmask_b32_e64 v157, v183, v157, s[4:5]
	v_cmp_gt_i32_e64 s[4:5], s33, v209
	v_subrev_u32_e32 v209, 30, v0
	v_cndmask_b32_e64 v142, v183, v142, s[6:7]
	v_cndmask_b32_e64 v158, v183, v158, s[6:7]
	v_cmp_gt_i32_e64 s[6:7], s33, v209
	v_subrev_u32_e32 v209, 29, v0
	v_cndmask_b32_e64 v143, v183, v143, s[8:9]
	v_cndmask_b32_e64 v159, v183, v159, s[8:9]
	v_cmp_gt_i32_e64 s[8:9], s33, v209
	s_or_b64 s[6:7], s[8:9], s[6:7]
	s_or_b64 s[4:5], s[6:7], s[4:5]
	s_or_b64 vcc, s[4:5], vcc
	v_add_u32_e32 v209, -16, v0
	v_cndmask_b32_e32 v144, v183, v144, vcc
	v_cndmask_b32_e32 v160, v183, v160, vcc
	v_cmp_gt_i32_e32 vcc, s33, v209
	v_add_u32_e32 v209, -15, v0
	v_cndmask_b32_e64 v145, v183, v145, s[4:5]
	v_cndmask_b32_e64 v161, v183, v161, s[4:5]
	v_cmp_gt_i32_e64 s[4:5], s33, v209
	v_add_u32_e32 v209, -14, v0
	v_add_u32_e32 v0, -13, v0
	v_cndmask_b32_e64 v147, v183, v147, s[8:9]
	v_cndmask_b32_e64 v146, v183, v146, s[6:7]
	v_cndmask_b32_e64 v162, v183, v162, s[6:7]
	v_cndmask_b32_e64 v163, v183, v163, s[8:9]
	v_cmp_gt_i32_e64 s[6:7], s33, v209
	v_cmp_gt_i32_e64 s[8:9], s33, v0
	s_or_b64 s[6:7], s[8:9], s[6:7]
	s_or_b64 s[4:5], s[6:7], s[4:5]
	s_or_b64 vcc, s[4:5], vcc
	v_cndmask_b32_e64 v151, v183, v151, s[8:9]
	v_cndmask_b32_e64 v150, v183, v150, s[6:7]
	v_cndmask_b32_e64 v149, v183, v149, s[4:5]
	v_cndmask_b32_e32 v148, v183, v148, vcc
	v_cndmask_b32_e64 v166, v183, v166, s[6:7]
	v_cndmask_b32_e64 v165, v183, v165, s[4:5]
	v_cndmask_b32_e32 v164, v183, v164, vcc
	v_cndmask_b32_e64 v167, v183, v167, s[8:9]

; template <int MODE>
; DI void attn_item(const Params& p, int item, char* smem, u16* gdst) {
;     ...
;         for (int s2 = 0; s2 < 2; ++s2) {
;           u32x4 pk;
;           pk[0] = cvtpk(s[qt][2 * s2][0], s[qt][2 * s2][1]);
;           pk[1] = cvtpk(s[qt][2 * s2][2], s[qt][2 * s2][3]);
;           pk[2] = cvtpk(s[qt][2 * s2 + 1][0], s[qt][2 * s2 + 1][1]);
;           pk[3] = cvtpk(s[qt][2 * s2 + 1][2], s[qt][2 * s2 + 1][3]);
;           pf[qt][s2] = __builtin_bit_cast(bf16x8, pk);
;         }
;       }
; #pragma unroll
;       for (int dt = 0; dt < 8; ++dt) {
; #pragma unroll
;         for (int s2 = 0; s2 < 2; ++s2) {
;           const u16* vp = sV + (dt * 16 + fr) * VSTR + fq * 4;
;           u32x2 v0 = *(const u32x2*)(vp + (2 * s2) * 16);
;           u32x2 v1 = *(const u32x2*)(vp + (2 * s2 + 1) * 16);
;           u32x4 vv = {v0[0], v0[1], v1[0], v1[1]};
;           bf16x8 vf = __builtin_bit_cast(bf16x8, vv);
;           o[0][dt] = __builtin_amdgcn_mfma_f32_16x16x32_bf16(vf, pf[0][s2], o[0][dt], 0, 0, 0);
;           o[1][dt] = __builtin_amdgcn_mfma_f32_16x16x32_bf16(vf, pf[1][s2], o[1][dt], 0, 0, 0);
;         }
;       }
.LBB0_1813:
	v_add_u32_e32 v150, s36, v198
	v_add_u32_e32 v150, 0x6000, v150
	v_add_u32_e32 v151, v150, v192
	v_add_u32_e32 v236, v150, v193
	ds_read_b64 v[232:233], v236
	ds_read_b64 v[234:235], v236 offset:32
	ds_read_b64 v[238:239], v236 offset:96
	ds_read_b64 v[236:237], v236 offset:64
	ds_read_b64 v[240:241], v151
	ds_read_b64 v[242:243], v151 offset:32
	ds_read_b64 v[244:245], v151 offset:64
	ds_read_b64 v[246:247], v151 offset:96
	v_add_u32_e32 v252, v150, v196
	ds_read_b64 v[248:249], v252
	ds_read_b64 v[250:251], v252 offset:32
	ds_read_b64 v[254:255], v252 offset:96
	ds_read_b64 v[252:253], v252 offset:64
	v_cvt_pk_bf16_f32 v210, v210, v211
	v_cvt_pk_bf16_f32 v211, v212, v155
	v_cvt_pk_bf16_f32 v212, v156, v157
	v_cvt_pk_bf16_f32 v156, v215, v216
	v_cvt_pk_bf16_f32 v215, v138, v139
	v_cvt_pk_bf16_f32 v139, v142, v143
	v_cvt_pk_bf16_f32 v216, v140, v141
	v_cvt_pk_bf16_f32 v140, v146, v147
	v_cvt_pk_bf16_f32 v138, v144, v145
	v_cvt_pk_bf16_f32 v213, v213, v214
	v_cvt_pk_bf16_f32 v214, v165, v167
	v_cvt_pk_bf16_f32 v217, v166, v217
	s_setprio 1
	s_waitcnt lgkmcnt(8)
	v_mfma_f32_16x16x32_bf16 v[128:131], v[232:235], v[210:213], v[128:131]
	v_cvt_pk_bf16_f32 v157, v162, v163
	v_cvt_pk_bf16_f32 v158, v158, v159
	v_cvt_pk_bf16_f32 v159, v160, v161
	v_mfma_f32_16x16x32_bf16 v[96:99], v[232:235], v[214:217], v[96:99]
	v_cvt_pk_bf16_f32 v141, v148, v149
	v_mfma_f32_16x16x32_bf16 v[128:131], v[236:239], v[156:159], v[128:131]
	v_add_f32_e32 v136, v136, v137
	v_add_f32_e32 v137, v153, v154
	v_fmac_f32_e32 v136, v202, v152
	v_fmac_f32_e32 v137, v204, v0
	v_mfma_f32_16x16x32_bf16 v[96:99], v[236:239], v[138:141], v[96:99]
	v_add_u32_e32 v236, v150, v197
	ds_read_b64 v[232:233], v236
	ds_read_b64 v[234:235], v236 offset:32
	ds_read_b64 v[238:239], v236 offset:96
	ds_read_b64 v[236:237], v236 offset:64
	v_add_f32_e32 v203, v203, v164
	v_add_f32_e32 v201, v201, v209
	v_mov_b32_e32 v204, v137
	v_mov_b32_e32 v202, v136
	s_waitcnt lgkmcnt(8)
	v_mfma_f32_16x16x32_bf16 v[124:127], v[240:243], v[210:213], v[124:127]
	v_mfma_f32_16x16x32_bf16 v[92:95], v[240:243], v[214:217], v[92:95]
	v_mfma_f32_16x16x32_bf16 v[124:127], v[244:247], v[156:159], v[124:127]
	v_mfma_f32_16x16x32_bf16 v[92:95], v[244:247], v[138:141], v[92:95]
	ds_read_b64 v[240:241], v151 offset:9216
	ds_read_b64 v[242:243], v151 offset:9248
	ds_read_b64 v[244:245], v151 offset:9280
	ds_read_b64 v[246:247], v151 offset:9312
	s_waitcnt lgkmcnt(8)
	v_mfma_f32_16x16x32_bf16 v[132:135], v[248:251], v[210:213], v[132:135]
	v_mfma_f32_16x16x32_bf16 v[100:103], v[248:251], v[214:217], v[100:103]
	v_mfma_f32_16x16x32_bf16 v[132:135], v[252:255], v[156:159], v[132:135]
	v_mfma_f32_16x16x32_bf16 v[100:103], v[252:255], v[138:141], v[100:103]
	ds_read_b64 v[248:249], v151 offset:11520
	ds_read_b64 v[250:251], v151 offset:11552
	ds_read_b64 v[252:253], v151 offset:11584
	ds_read_b64 v[254:255], v151 offset:11616
	s_waitcnt lgkmcnt(8)
	v_mfma_f32_16x16x32_bf16 v[120:123], v[232:235], v[210:213], v[120:123]
	v_mfma_f32_16x16x32_bf16 v[88:91], v[232:235], v[214:217], v[88:91]
	v_mfma_f32_16x16x32_bf16 v[120:123], v[236:239], v[156:159], v[120:123]
	v_mfma_f32_16x16x32_bf16 v[88:91], v[236:239], v[138:141], v[88:91]
	ds_read_b64 v[232:233], v151 offset:13824
	ds_read_b64 v[234:235], v151 offset:13856
	ds_read_b64 v[236:237], v151 offset:13888
	ds_read_b64 v[238:239], v151 offset:13920
	s_waitcnt lgkmcnt(8)
	v_mfma_f32_16x16x32_bf16 v[104:107], v[240:243], v[210:213], v[104:107]
	v_mfma_f32_16x16x32_bf16 v[72:75], v[240:243], v[214:217], v[72:75]
	v_mfma_f32_16x16x32_bf16 v[104:107], v[244:247], v[156:159], v[104:107]
	v_mfma_f32_16x16x32_bf16 v[72:75], v[244:247], v[138:141], v[72:75]
	ds_read_b64 v[240:241], v151 offset:16128
	ds_read_b64 v[242:243], v151 offset:16160
	ds_read_b64 v[244:245], v151 offset:16192
	ds_read_b64 v[246:247], v151 offset:16224
	s_waitcnt lgkmcnt(8)
	v_mfma_f32_16x16x32_bf16 v[108:111], v[248:251], v[210:213], v[108:111]
	v_mfma_f32_16x16x32_bf16 v[76:79], v[248:251], v[214:217], v[76:79]
	v_mfma_f32_16x16x32_bf16 v[108:111], v[252:255], v[156:159], v[108:111]
	v_mfma_f32_16x16x32_bf16 v[76:79], v[252:255], v[138:141], v[76:79]
	s_waitcnt lgkmcnt(4)
	v_mfma_f32_16x16x32_bf16 v[112:115], v[232:235], v[210:213], v[112:115]
	v_mfma_f32_16x16x32_bf16 v[80:83], v[232:235], v[214:217], v[80:83]
	v_mfma_f32_16x16x32_bf16 v[112:115], v[236:239], v[156:159], v[112:115]
	v_mfma_f32_16x16x32_bf16 v[80:83], v[236:239], v[138:141], v[80:83]
	s_waitcnt lgkmcnt(0)
	v_mfma_f32_16x16x32_bf16 v[116:119], v[240:243], v[210:213], v[116:119]
	v_mfma_f32_16x16x32_bf16 v[84:87], v[240:243], v[214:217], v[84:87]
	v_mfma_f32_16x16x32_bf16 v[116:119], v[244:247], v[156:159], v[116:119]
	v_mfma_f32_16x16x32_bf16 v[84:87], v[244:247], v[138:141], v[84:87]
	s_setprio 0
